# GU GEMM last half-round split into 128-row half-units over all 32 WGs of the XCD (skip second-A-half MFMAs + epilogue half)
# baseline (speedup 1.0000x reference)
; #define PG8_STAGE(bufoff, gbase, voff) do { _Pragma("unroll") for (int _i = 0; _i < 2; ++_i) \
;         __builtin_amdgcn_global_load_lds((const unsigned*)((const char*)(gbase) + (voff)[_i]), (PG8_LAS unsigned*)(lds + (bufoff) + ldsw + _i * 8192), 16, 0, 0); } while (0)
; #define PG8_WAIT_V(n) asm volatile("s_waitcnt vmcnt(" #n ")" ::: "memory")
; #define PG8_BAR __builtin_amdgcn_s_barrier()
; template <class Epi, class Sched, bool ALIGN_EPI = false, bool SP2 = false, bool HALFM = false>
; __device__ __forceinline__ void gemm_phase(PG8_LAS unsigned char* lds, const Gemm g, const Sched& S, const Epi& E) {
;     ...
;     for (int i = 0; i < 2; ++i) { int R, C; stage_rc(tid * 16 + i * 8192, R, C); const int Rb = Epi::PERM ? ((R & ~31) + perm32(R & 31)) : R;
;         voffA[i] = (unsigned)(R * K + C) * 2u; voffB[i] = (unsigned)(Rb * K + C) * 2u; }
;     const size_t kstep = (size_t)(BK * 2);
;     const size_t hstep = (size_t)HALF * K * 2;
;     const size_t tstep = 2 * hstep;
;     const unsigned ldsw = (unsigned)wid * 1024u;
;     const int aoff = lds_byte(wr * 64 + fr, fq * 8), boff = lds_byte(wc * 32 + fr, fq * 8);
;     ...
;     if constexpr (SP2) {
;         PG8_STAGE(PG8_SB(0, 0), cB, voffB); PG8_STAGE(PG8_SB(0, 1), cB + hstep, voffB); PG8_STAGE(PG8_SA(0, 0), cA, voffA); PG8_STAGE(PG8_SA(0, 1), cA + hstep, voffA);
;         if (wr == 1) PG8_BAR;
;         PG8_WAIT_V(2); PG8_BAR;
;         PG8_STAGE(PG8_SB(1, 0), cB + kstep, voffB); PG8_STAGE(PG8_SA(1, 0), cA + kstep, voffA); PG8_STAGE(PG8_SB(1, 1), cB + hstep + kstep, voffB);
;         PG8_WAIT_V(6); PG8_BAR;
.LBB0_172:
	v_readlane_b32 s22, v254, 5
	s_lshl_b32 s5, s5, 5
	v_mov_b32_e32 v131, v81
	v_readlane_b32 s23, v254, 6
	s_and_b32 s12, s5, 0x60
	s_add_i32 m0, s47, 0x18000
	v_lshl_add_u64 v[0:1], v[0:1], 0, s[82:83]
	v_lshl_add_u64 v[12:13], s[22:23], 0, v[130:131]
	v_mov_b32_e32 v133, v81
	s_lshl_b32 s9, s8, 13
	s_lshl_b32 s5, s12, 7
	s_waitcnt vmcnt(2)
	s_barrier
	global_load_lds_dwordx4 v[0:1], off
	v_lshl_add_u64 v[0:1], v[2:3], 0, s[82:83]
	s_add_i32 m0, s47, 0x1a000
	s_add_i32 s51, s47, 0x8000
	s_add_i32 s52, s47, 0xa000
	v_lshl_add_u64 v[14:15], s[22:23], 0, v[132:133]
	global_load_lds_dwordx4 v[0:1], off
	v_lshl_add_u64 v[0:1], v[12:13], 0, s[82:83]
	s_mov_b32 m0, s51
	s_add_u32 s10, s24, 0x40080
	global_load_lds_dwordx4 v[0:1], off
	v_lshl_add_u64 v[0:1], v[14:15], 0, s[82:83]
	s_mov_b32 m0, s52
	s_addc_u32 s11, s25, 0
	global_load_lds_dwordx4 v[0:1], off
	s_add_i32 m0, s47, 0x1c000
	v_lshl_add_u64 v[0:1], s[10:11], 0, v[80:81]
	global_load_lds_dwordx4 v[0:1], off
	v_lshl_add_u64 v[0:1], s[10:11], 0, v[134:135]
	s_add_i32 m0, s47, 0x1e000
	s_cmpk_lt_u32 s4, 0x100
	global_load_lds_dwordx4 v[0:1], off
	v_lshrrev_b32_e32 v1, 1, v4
	v_and_b32_e32 v1, 24, v1
	v_and_b32_e32 v0, 15, v4
	v_lshlrev_b32_e32 v2, 1, v1
	v_lshl_or_b32 v142, s8, 6, v0
	v_lshl_or_b32 v2, v0, 6, v2
	v_lshlrev_b32_e32 v0, 2, v0
	v_and_b32_e32 v3, 32, v0
	v_bitop3_b32 v143, v2, s5, v3 bitop3:0xde
	s_cselect_b64 s[4:5], -1, 0
	s_lshl_b32 s8, s8, 8
	s_add_i32 s8, s8, 0
	s_add_i32 s8, s8, 0x24900
	v_add_u32_e32 v145, s8, v0
	v_lshlrev_b32_e32 v0, 14, v5
	v_and_b32_e32 v0, 0xffff8000, v0
	v_or_b32_e32 v144, s12, v1
	v_lshl_add_u32 v0, v6, 11, v0
	v_and_b32_e32 v1, 1, v5
	v_lshl_or_b32 v0, v1, 6, v0
	v_lshl_add_u32 v136, v7, 1, v0
	v_lshlrev_b32_e32 v0, 14, v8
	v_and_b32_e32 v0, 0xffff8000, v0
	s_waitcnt vmcnt(6)
	v_lshl_add_u32 v0, v9, 11, v0
	v_and_b32_e32 v1, 1, v8
	v_bitop3_b32 v4, v2, s9, v3 bitop3:0xde
	v_lshl_or_b32 v0, v1, 6, v0
	v_readlane_b32 s8, v254, 2
	v_mov_b32_e32 v137, v81
	v_lshl_add_u32 v138, v10, 1, v0
	v_mov_b32_e32 v139, v81
	s_mov_b32 s55, 0
	v_add_u32_e32 v146, 0, v4
	v_readlane_b32 s56, v253, 63
	s_mov_b32 s57, s8
	s_mov_b32 s53, 0
	s_barrier
	v_readlane_b32 s9, v254, 3
	s_mov_b32 s99, 0
	s_mov_b32 s101, 0
	s_branch .LBB0_175

; template <int MODE> __device__ __forceinline__ UD decode(int j) { UD x; x.u = j & 7; int bh; if (MODE == 1) { bh = j >> 4; x.br = 1 + ((j >> 3) & 1); } else { bh = j >> 3; x.br = 0; } x.b = bh / NH; x.h = bh % NH; return x; }
;     __host__ __device__ bool next(int i, Unit& u) const {
;         const long L = (long)i * G + c; if (i >= imax || L >= nwg) return false;
;         decode(L, u); u.par = i & 1; u.roff = 0; return true;
; template <class Epi, class Sched, bool ALIGN_EPI = false, bool SP2 = false, bool HALFM = false>
; __device__ __forceinline__ void gemm_phase(PG8_LAS unsigned char* lds, const Gemm g, const Sched& S, const Epi& E) {
;     ...
; #pragma unroll
;         for (int a = 0; a < 2; ++a)
; #pragma unroll
;             for (int b = 0; b < 2; ++b)
; #pragma unroll
;                 for (int m = 0; m < 4; ++m)
; #pragma unroll
;                     for (int n = 0; n < 2; ++n) acc[a][b][m][n] = (f32x4){0.f, 0.f, 0.f, 0.f};
;         cur = nxt; cA = nA; cB = nB; ++ui;
.LBB0_174:
	s_andn2_b64 vcc, exec, s[18:19]
	s_mov_b32 s99, s98
	s_mov_b32 s101, s100
	s_mov_b32 s55, s54
	s_mov_b32 s56, s8
	s_mov_b32 s57, s10
	s_mov_b64 s[24:25], s[14:15]
	s_mov_b64 s[22:23], s[12:13]
	s_cbranch_vccz .LBB0_188
.LBB0_175:
	s_mov_b32 s9, s53
	s_add_i32 s53, s53, 1
	s_mul_i32 s11, s53, s39
	s_mul_hi_u32 s12, s53, s72
	s_add_i32 s11, s12, s11
	s_mul_i32 s12, s53, s72
	s_add_u32 s12, s12, s33
	s_addc_u32 s13, s11, s38
	s_and_b32 s100, s33, 0x80
	s_cmp_eq_u32 s53, 5
	s_cselect_b32 s100, s100, 0
	s_cselect_b32 s98, 1, 0
	s_cmpk_eq_i32 s72, 0x100
	s_cselect_b32 s100, s100, 0
	s_cselect_b32 s98, s98, 0
	s_sub_u32 s12, s12, s100
	s_subb_u32 s13, s13, 0
	s_cmp_gt_u32 s9, 0x3ffffffe
	s_cselect_b64 s[14:15], -1, 0
	v_cmp_gt_i64_e32 vcc, s[12:13], v[154:155]
	s_or_b64 s[18:19], s[14:15], vcc
	s_and_b64 vcc, exec, s[18:19]
	s_cbranch_vccnz .LBB0_177
	s_ashr_i32 s8, s12, 31
	s_lshr_b32 s8, s8, 29
	s_add_i32 s8, s12, s8
	s_ashr_i32 s9, s8, 3
	s_and_b32 s8, s8, -8
	s_sub_i32 s8, s12, s8
	s_cmp_lt_i32 s8, 0
	s_movk_i32 s10, 0xb1
	s_cselect_b32 s10, s10, 0xb0
	s_mul_i32 s8, s8, s10
	s_add_i32 s8, s8, s9
	s_mul_hi_i32 s9, s8, 0x2e8ba2e9
	s_lshr_b32 s10, s9, 31
	s_ashr_i32 s9, s9, 5
	s_add_i32 s9, s9, s10
	s_lshl_b32 s10, s9, 3
	s_sub_i32 s11, 64, s10
	s_min_i32 s11, s11, 8
	s_abs_i32 s12, s11
	v_cvt_f32_u32_e32 v0, s12
	s_sub_i32 s14, 0, s12
	s_mulk_i32 s9, 0xb0
	s_sub_i32 s9, s8, s9
	v_rcp_iflag_f32_e32 v0, v0
	s_abs_i32 s8, s9
	s_xor_b32 s13, s9, s11
	s_ashr_i32 s13, s13, 31
	v_mul_f32_e32 v0, 0x4f7ffffe, v0
	v_cvt_u32_f32_e32 v0, v0
	s_nop 0
	v_readfirstlane_b32 s15, v0
	s_mul_i32 s14, s14, s15
	s_mul_hi_u32 s14, s15, s14
	s_add_i32 s15, s15, s14
	s_mul_hi_u32 s14, s8, s15
	s_mul_i32 s15, s14, s12
	s_sub_i32 s8, s8, s15
	s_add_i32 s16, s14, 1
	s_sub_i32 s15, s8, s12
	s_cmp_ge_u32 s8, s12
	s_cselect_b32 s14, s16, s14
	s_cselect_b32 s8, s15, s8
	s_add_i32 s15, s14, 1
	s_cmp_ge_u32 s8, s12
	s_cselect_b32 s8, s15, s14
	s_xor_b32 s8, s8, s13
	s_sub_i32 s8, s8, s13
	s_mul_i32 s11, s8, s11
	s_sub_i32 s9, s9, s11
	s_add_i32 s10, s10, s9
	s_and_b32 s54, s53, 1
.LBB0_177:
	s_ashr_i32 s11, s10, 31
	s_xor_b64 s[16:17], s[18:19], -1
	s_lshl_b32 s12, s10, 8
	s_add_i32 s12, s12, s100
	s_mov_b32 s13, 0
	s_lshl_b64 s[12:13], s[12:13], 11
	s_add_u32 s12, s30, s12
	s_addc_u32 s13, s31, s13
	s_and_b64 s[14:15], exec, s[18:19]
	s_cselect_b32 s11, s23, s13
	s_cselect_b32 s58, s22, s12
	s_ashr_i32 s9, s8, 31
	s_lshl_b64 s[14:15], s[8:9], 19
	s_add_u32 s14, s29, s14
	s_addc_u32 s15, s45, s15
	s_and_b64 s[20:21], exec, s[18:19]
	s_cselect_b32 s9, s25, s15
	s_cselect_b32 s59, s24, s14
	s_lshl_b32 s60, s10, 8
	s_lshl_b32 s26, s54, 10
	s_cmp_eq_u32 s10, s28
	s_cselect_b64 s[20:21], -1, 0
	s_add_i32 s61, s26, 0
	s_add_i32 s61, s61, 0x24900
	s_add_u32 s22, s22, 0x40080
	s_addc_u32 s23, s23, 0
	s_add_u32 s62, s24, 0x100
	v_mov_b32_e32 v0, 0
	s_addc_u32 s63, s25, 0
	s_mov_b32 s64, -2
	v_mov_b32_e32 v1, v0
	v_mov_b32_e32 v2, v0
	v_mov_b32_e32 v3, v0
	v_mov_b32_e32 v4, v0
	v_mov_b32_e32 v5, v0
	v_mov_b32_e32 v6, v0
	v_mov_b32_e32 v7, v0
	v_mov_b32_e32 v16, v0
	v_mov_b32_e32 v17, v0
	v_mov_b32_e32 v18, v0
	v_mov_b32_e32 v19, v0
	v_mov_b32_e32 v20, v0
	v_mov_b32_e32 v21, v0
	v_mov_b32_e32 v22, v0
	v_mov_b32_e32 v23, v0
	v_mov_b32_e32 v32, v0
	v_mov_b32_e32 v33, v0
	v_mov_b32_e32 v34, v0
	v_mov_b32_e32 v35, v0
	v_mov_b32_e32 v36, v0
	v_mov_b32_e32 v37, v0
	v_mov_b32_e32 v38, v0
	v_mov_b32_e32 v39, v0
	v_mov_b32_e32 v48, v0
	v_mov_b32_e32 v49, v0
	v_mov_b32_e32 v50, v0
	v_mov_b32_e32 v51, v0
	v_mov_b32_e32 v52, v0
	v_mov_b32_e32 v53, v0
	v_mov_b32_e32 v54, v0
	v_mov_b32_e32 v55, v0
	v_mov_b32_e32 v8, v0
	v_mov_b32_e32 v9, v0
	v_mov_b32_e32 v10, v0
	v_mov_b32_e32 v11, v0
	v_mov_b32_e32 v12, v0
	v_mov_b32_e32 v13, v0
	v_mov_b32_e32 v14, v0
	v_mov_b32_e32 v15, v0
	v_mov_b32_e32 v24, v0
	v_mov_b32_e32 v25, v0
	v_mov_b32_e32 v26, v0
	v_mov_b32_e32 v27, v0
	v_mov_b32_e32 v28, v0
	v_mov_b32_e32 v29, v0
	v_mov_b32_e32 v30, v0
	v_mov_b32_e32 v31, v0
	v_mov_b32_e32 v40, v0
	v_mov_b32_e32 v41, v0
	v_mov_b32_e32 v42, v0
	v_mov_b32_e32 v43, v0
	v_mov_b32_e32 v44, v0
	v_mov_b32_e32 v45, v0
	v_mov_b32_e32 v46, v0
	v_mov_b32_e32 v47, v0
	v_mov_b32_e32 v56, v0
	v_mov_b32_e32 v57, v0
	v_mov_b32_e32 v58, v0
	v_mov_b32_e32 v59, v0
	v_mov_b32_e32 v60, v0
	v_mov_b32_e32 v61, v0
	v_mov_b32_e32 v62, v0
	v_mov_b32_e32 v63, v0
	v_mov_b32_e32 v64, v0
	v_mov_b32_e32 v65, v0
	v_mov_b32_e32 v66, v0
	v_mov_b32_e32 v67, v0
	v_mov_b32_e32 v68, v0
	v_mov_b32_e32 v69, v0
	v_mov_b32_e32 v70, v0
	v_mov_b32_e32 v71, v0
	v_mov_b32_e32 v82, v0
	v_mov_b32_e32 v83, v0
	v_mov_b32_e32 v84, v0
	v_mov_b32_e32 v85, v0
	v_mov_b32_e32 v86, v0
	v_mov_b32_e32 v87, v0
	v_mov_b32_e32 v88, v0
	v_mov_b32_e32 v89, v0
	v_mov_b32_e32 v98, v0
	v_mov_b32_e32 v99, v0
	v_mov_b32_e32 v100, v0
	v_mov_b32_e32 v101, v0
	v_mov_b32_e32 v102, v0
	v_mov_b32_e32 v103, v0
	v_mov_b32_e32 v104, v0
	v_mov_b32_e32 v105, v0
	v_mov_b32_e32 v114, v0
	v_mov_b32_e32 v115, v0
	v_mov_b32_e32 v116, v0
	v_mov_b32_e32 v117, v0
	v_mov_b32_e32 v118, v0
	v_mov_b32_e32 v119, v0
	v_mov_b32_e32 v120, v0
	v_mov_b32_e32 v121, v0
	v_mov_b32_e32 v72, v0
	v_mov_b32_e32 v73, v0
	v_mov_b32_e32 v74, v0
	v_mov_b32_e32 v75, v0
	v_mov_b32_e32 v76, v0
	v_mov_b32_e32 v77, v0
	v_mov_b32_e32 v78, v0
	v_mov_b32_e32 v79, v0
	v_mov_b32_e32 v90, v0
	v_mov_b32_e32 v91, v0
	v_mov_b32_e32 v92, v0
	v_mov_b32_e32 v93, v0
	v_mov_b32_e32 v94, v0
	v_mov_b32_e32 v95, v0
	v_mov_b32_e32 v96, v0
	v_mov_b32_e32 v97, v0
	v_mov_b32_e32 v106, v0
	v_mov_b32_e32 v107, v0
	v_mov_b32_e32 v108, v0
	v_mov_b32_e32 v109, v0
	v_mov_b32_e32 v110, v0
	v_mov_b32_e32 v111, v0
	v_mov_b32_e32 v112, v0
	v_mov_b32_e32 v113, v0
	v_mov_b32_e32 v122, v0
	v_mov_b32_e32 v123, v0
	v_mov_b32_e32 v124, v0
	v_mov_b32_e32 v125, v0
	v_mov_b32_e32 v126, v0
	v_mov_b32_e32 v127, v0
	v_mov_b32_e32 v128, v0
	v_mov_b32_e32 v129, v0
	s_branch .LBB0_180

; #define PG8_STAGE(bufoff, gbase, voff) do { _Pragma("unroll") for (int _i = 0; _i < 2; ++_i) \
;         __builtin_amdgcn_global_load_lds((const unsigned*)((const char*)(gbase) + (voff)[_i]), (PG8_LAS unsigned*)(lds + (bufoff) + ldsw + _i * 8192), 16, 0, 0); } while (0)
; #define PG8_LDA(dst, b, h) do { _Pragma("unroll") for (int m = 0; m < 4; ++m) _Pragma("unroll") for (int k = 0; k < 2; ++k) dst[m][k] = *(const PG8_LAS bf16x8*)(lds + PG8_SA(b, h) + aoff + m * 2048 + k * 1024); } while (0)
; #define PG8_LDB(dst, b, h) do { _Pragma("unroll") for (int n = 0; n < 2; ++n) _Pragma("unroll") for (int k = 0; k < 2; ++k) dst[n][k] = *(const PG8_LAS bf16x8*)(lds + PG8_SB(b, h) + boff + n * 2048 + k * 1024); } while (0)
; #define PG8_MMA(ai, bj, At, Bt) do { __builtin_amdgcn_s_setprio(1); _Pragma("unroll") for (int m = 0; m < 4; ++m) _Pragma("unroll") for (int n = 0; n < 2; ++n) _Pragma("unroll") for (int k = 0; k < 2; ++k) \
;         acc[ai][bj][m][n] = __builtin_amdgcn_mfma_f32_16x16x32_bf16(Bt[n][k], At[m][k], acc[ai][bj][m][n], 0, 0, 0); __builtin_amdgcn_s_setprio(0); } while (0)
; #define PG8_WAIT_V(n) asm volatile("s_waitcnt vmcnt(" #n ")" ::: "memory")
; #define PG8_WAIT_L(n) asm volatile("s_waitcnt lgkmcnt(" #n ")" ::: "memory")
; #define PG8_BAR __builtin_amdgcn_s_barrier()
; #define PG8_SCHED __builtin_amdgcn_sched_barrier(0)
; template <class Epi, class Sched, bool ALIGN_EPI = false, bool SP2 = false, bool HALFM = false>
; __device__ __forceinline__ void gemm_phase(PG8_LAS unsigned char* lds, const Gemm g, const Sched& S, const Epi& E) {
;     ...
;             PG8_LDB(B0, 0, 0); PG8_LDB(B1, 0, 1); PG8_SCHED; PG8_LDA(At, 0, 0); PG8_STAGE(PG8_SA(1, 1), a1 + hstep, voffA);
;             PG8_WAIT_V(8); PG8_WAIT_L(0); PG8_BAR; PG8_MMA(0, 0, At, B0); PG8_MMA(0, 1, At, B1); PG8_BAR; PG8_SCHED;
;             if constexpr (!HALFM) PG8_LDA(At, 0, 1); PG8_STAGE(PG8_SB(0, 0), b2, voffB); PG8_STAGE(PG8_SB(0, 1), b2 + hstep, voffB); PG8_STAGE(PG8_SA(0, 0), a2, voffA);
;             PG8_WAIT_V(8); PG8_WAIT_L(0); PG8_BAR; if constexpr (!HALFM) { PG8_MMA(1, 0, At, B0); PG8_MMA(1, 1, At, B1); } PG8_BAR; PG8_SCHED;
.LBB0_179:
	s_add_u32 s26, s22, 0xfffc0080
	s_addc_u32 s27, s23, -1
	s_and_b64 s[24:25], s[24:25], exec
	s_cselect_b32 s27, s27, s11
	s_cselect_b32 s26, s26, s58
	s_cselect_b32 s25, s63, s9
	s_cselect_b32 s24, s62, s59
	s_add_i32 s65, 0, 0x10000
	v_add_u32_e32 v140, s65, v143
	s_add_i32 s68, 0, 0x14000
	ds_read_b128 v[148:151], v140
	ds_read_b128 v[160:163], v140 offset:1024
	ds_read_b128 v[164:167], v140 offset:2048
	ds_read_b128 v[168:171], v140 offset:3072
	v_add_u32_e32 v140, s68, v143
	ds_read_b128 v[172:175], v140
	ds_read_b128 v[176:179], v140 offset:1024
	ds_read_b128 v[180:183], v140 offset:2048
	ds_read_b128 v[184:187], v140 offset:3072
	v_lshl_add_u64 v[140:141], s[22:23], 0, v[136:137]
	s_add_i32 m0, s47, 0xc000
	ds_read_b128 v[202:205], v146
	ds_read_b128 v[206:209], v146 offset:1024
	ds_read_b128 v[210:213], v146 offset:2048
	ds_read_b128 v[214:217], v146 offset:3072
	ds_read_b128 v[218:221], v146 offset:4096
	ds_read_b128 v[222:225], v146 offset:5120
	ds_read_b128 v[226:229], v146 offset:6144
	ds_read_b128 v[230:233], v146 offset:7168
	global_load_lds_dwordx4 v[140:141], off
	v_lshl_add_u64 v[140:141], s[22:23], 0, v[138:139]
	s_add_i32 m0, s47, 0xe000
	s_nop 0
	global_load_lds_dwordx4 v[140:141], off
	s_waitcnt vmcnt(8)
	s_waitcnt lgkmcnt(0)
	s_barrier
	s_setprio 1
	s_waitcnt lgkmcnt(0)
	v_mfma_f32_16x16x32_bf16 v[126:129], v[148:151], v[202:205], v[126:129]
	v_mfma_f32_16x16x32_bf16 v[122:125], v[164:167], v[202:205], v[122:125]
	v_mfma_f32_16x16x32_bf16 v[110:113], v[148:151], v[210:213], v[110:113]
	v_mfma_f32_16x16x32_bf16 v[106:109], v[164:167], v[210:213], v[106:109]
	v_mfma_f32_16x16x32_bf16 v[94:97], v[148:151], v[218:221], v[94:97]
	v_mfma_f32_16x16x32_bf16 v[90:93], v[164:167], v[218:221], v[90:93]
	v_mfma_f32_16x16x32_bf16 v[76:79], v[148:151], v[226:229], v[76:79]
	v_mfma_f32_16x16x32_bf16 v[72:75], v[164:167], v[226:229], v[72:75]
	v_mfma_f32_16x16x32_bf16 v[126:129], v[160:163], v[206:209], v[126:129]
	v_mfma_f32_16x16x32_bf16 v[122:125], v[168:171], v[206:209], v[122:125]
	v_mfma_f32_16x16x32_bf16 v[110:113], v[160:163], v[214:217], v[110:113]
	v_mfma_f32_16x16x32_bf16 v[106:109], v[168:171], v[214:217], v[106:109]
	v_mfma_f32_16x16x32_bf16 v[94:97], v[160:163], v[222:225], v[94:97]
	v_mfma_f32_16x16x32_bf16 v[90:93], v[168:171], v[222:225], v[90:93]
	v_mfma_f32_16x16x32_bf16 v[76:79], v[160:163], v[230:233], v[76:79]
	v_mfma_f32_16x16x32_bf16 v[72:75], v[168:171], v[230:233], v[72:75]
	s_setprio 0
	s_setprio 1
	v_mfma_f32_16x16x32_bf16 v[118:121], v[172:175], v[202:205], v[118:121]
	v_mfma_f32_16x16x32_bf16 v[114:117], v[180:183], v[202:205], v[114:117]
	v_mfma_f32_16x16x32_bf16 v[102:105], v[172:175], v[210:213], v[102:105]
	v_mfma_f32_16x16x32_bf16 v[98:101], v[180:183], v[210:213], v[98:101]
	v_mfma_f32_16x16x32_bf16 v[86:89], v[172:175], v[218:221], v[86:89]
	v_mfma_f32_16x16x32_bf16 v[82:85], v[180:183], v[218:221], v[82:85]
	v_mfma_f32_16x16x32_bf16 v[68:71], v[172:175], v[226:229], v[68:71]
	v_mfma_f32_16x16x32_bf16 v[64:67], v[180:183], v[226:229], v[64:67]
	v_mfma_f32_16x16x32_bf16 v[118:121], v[176:179], v[206:209], v[118:121]
	v_mfma_f32_16x16x32_bf16 v[114:117], v[184:187], v[206:209], v[114:117]
	v_mfma_f32_16x16x32_bf16 v[102:105], v[176:179], v[214:217], v[102:105]
	v_mfma_f32_16x16x32_bf16 v[98:101], v[184:187], v[214:217], v[98:101]
	v_mfma_f32_16x16x32_bf16 v[86:89], v[176:179], v[222:225], v[86:89]
	v_mfma_f32_16x16x32_bf16 v[82:85], v[184:187], v[222:225], v[82:85]
	v_mfma_f32_16x16x32_bf16 v[68:71], v[176:179], v[230:233], v[68:71]
	v_mfma_f32_16x16x32_bf16 v[64:67], v[184:187], v[230:233], v[64:67]
	s_setprio 0
	s_barrier
	s_add_i32 s65, s65, s46
	v_lshl_add_u64 v[140:141], s[24:25], 0, v[80:81]
	s_mov_b32 m0, s65
	ds_read_b128 v[202:205], v146 offset:16384
	ds_read_b128 v[206:209], v146 offset:17408
	ds_read_b128 v[210:213], v146 offset:18432
	ds_read_b128 v[214:217], v146 offset:19456
	ds_read_b128 v[218:221], v146 offset:20480
	ds_read_b128 v[222:225], v146 offset:21504
	ds_read_b128 v[226:229], v146 offset:22528
	ds_read_b128 v[230:233], v146 offset:23552
	global_load_lds_dwordx4 v[140:141], off
	s_add_i32 m0, s65, 0x2000
	s_add_u32 s66, s24, 0x40000
	v_lshl_add_u64 v[152:153], s[24:25], 0, v[134:135]
	s_addc_u32 s67, s25, 0
	s_add_i32 s65, s68, s46
	global_load_lds_dwordx4 v[152:153], off
	v_lshl_add_u64 v[188:189], s[66:67], 0, v[80:81]
	s_mov_b32 m0, s65
	v_lshl_add_u64 v[196:197], s[26:27], 0, v[132:133]
	global_load_lds_dwordx4 v[188:189], off
	v_lshl_add_u64 v[188:189], s[66:67], 0, v[134:135]
	s_add_i32 m0, s65, 0x2000
	s_nop 0
	global_load_lds_dwordx4 v[188:189], off
	v_lshl_add_u64 v[188:189], s[26:27], 0, v[130:131]
	s_mov_b32 m0, s47
	s_nop 0
	global_load_lds_dwordx4 v[188:189], off
	s_mov_b32 m0, s48
	s_nop 0
	global_load_lds_dwordx4 v[196:197], off
	s_waitcnt vmcnt(8)
	s_waitcnt lgkmcnt(0)
	s_barrier
	s_cmp_lg_u32 s99, 0
	s_cbranch_scc1 .Lgu_half_skip0
; #define PG8_STAGE(bufoff, gbase, voff) do { _Pragma("unroll") for (int _i = 0; _i < 2; ++_i) \
;         __builtin_amdgcn_global_load_lds((const unsigned*)((const char*)(gbase) + (voff)[_i]), (PG8_LAS unsigned*)(lds + (bufoff) + ldsw + _i * 8192), 16, 0, 0); } while (0)
; #define PG8_LDA(dst, b, h) do { _Pragma("unroll") for (int m = 0; m < 4; ++m) _Pragma("unroll") for (int k = 0; k < 2; ++k) dst[m][k] = *(const PG8_LAS bf16x8*)(lds + PG8_SA(b, h) + aoff + m * 2048 + k * 1024); } while (0)
; #define PG8_LDB(dst, b, h) do { _Pragma("unroll") for (int n = 0; n < 2; ++n) _Pragma("unroll") for (int k = 0; k < 2; ++k) dst[n][k] = *(const PG8_LAS bf16x8*)(lds + PG8_SB(b, h) + boff + n * 2048 + k * 1024); } while (0)
; #define PG8_MMA(ai, bj, At, Bt) do { __builtin_amdgcn_s_setprio(1); _Pragma("unroll") for (int m = 0; m < 4; ++m) _Pragma("unroll") for (int n = 0; n < 2; ++n) _Pragma("unroll") for (int k = 0; k < 2; ++k) \
;         acc[ai][bj][m][n] = __builtin_amdgcn_mfma_f32_16x16x32_bf16(Bt[n][k], At[m][k], acc[ai][bj][m][n], 0, 0, 0); __builtin_amdgcn_s_setprio(0); } while (0)
; #define PG8_WAIT_V(n) asm volatile("s_waitcnt vmcnt(" #n ")" ::: "memory")
; #define PG8_WAIT_L(n) asm volatile("s_waitcnt lgkmcnt(" #n ")" ::: "memory")
; #define PG8_BAR __builtin_amdgcn_s_barrier()
; #define PG8_SCHED __builtin_amdgcn_sched_barrier(0)
; template <class Epi, class Sched, bool ALIGN_EPI = false, bool SP2 = false, bool HALFM = false>
; __device__ __forceinline__ void gemm_phase(PG8_LAS unsigned char* lds, const Gemm g, const Sched& S, const Epi& E) {
;     ...
;             PG8_WAIT_V(8); PG8_WAIT_L(0); PG8_BAR; if constexpr (!HALFM) { PG8_MMA(1, 0, At, B0); PG8_MMA(1, 1, At, B1); } PG8_BAR; PG8_SCHED;
;             PG8_LDB(B0, 1, 0); PG8_LDB(B1, 1, 1); PG8_SCHED; PG8_LDA(At, 1, 0); PG8_STAGE(PG8_SA(0, 1), a2 + hstep, voffA);
;             PG8_WAIT_V(8); PG8_WAIT_L(0); PG8_BAR; PG8_MMA(0, 0, At, B0); PG8_MMA(0, 1, At, B1); PG8_BAR; PG8_SCHED;
	s_setprio 1
	s_waitcnt lgkmcnt(0)
	v_mfma_f32_16x16x32_bf16 v[60:63], v[148:151], v[202:205], v[60:63]
	v_mfma_f32_16x16x32_bf16 v[56:59], v[164:167], v[202:205], v[56:59]
	v_mfma_f32_16x16x32_bf16 v[44:47], v[148:151], v[210:213], v[44:47]
	v_mfma_f32_16x16x32_bf16 v[40:43], v[164:167], v[210:213], v[40:43]
	v_mfma_f32_16x16x32_bf16 v[28:31], v[148:151], v[218:221], v[28:31]
	v_mfma_f32_16x16x32_bf16 v[24:27], v[164:167], v[218:221], v[24:27]
	v_mfma_f32_16x16x32_bf16 v[12:15], v[148:151], v[226:229], v[12:15]
	v_mfma_f32_16x16x32_bf16 v[8:11], v[164:167], v[226:229], v[8:11]
	v_mfma_f32_16x16x32_bf16 v[60:63], v[160:163], v[206:209], v[60:63]
	v_mfma_f32_16x16x32_bf16 v[56:59], v[168:171], v[206:209], v[56:59]
	v_mfma_f32_16x16x32_bf16 v[44:47], v[160:163], v[214:217], v[44:47]
	v_mfma_f32_16x16x32_bf16 v[40:43], v[168:171], v[214:217], v[40:43]
	v_mfma_f32_16x16x32_bf16 v[28:31], v[160:163], v[222:225], v[28:31]
	v_mfma_f32_16x16x32_bf16 v[24:27], v[168:171], v[222:225], v[24:27]
	v_mfma_f32_16x16x32_bf16 v[12:15], v[160:163], v[230:233], v[12:15]
	v_mfma_f32_16x16x32_bf16 v[8:11], v[168:171], v[230:233], v[8:11]
	s_setprio 0
	s_setprio 1
	v_mfma_f32_16x16x32_bf16 v[52:55], v[172:175], v[202:205], v[52:55]
	v_mfma_f32_16x16x32_bf16 v[48:51], v[180:183], v[202:205], v[48:51]
	v_mfma_f32_16x16x32_bf16 v[36:39], v[172:175], v[210:213], v[36:39]
	v_mfma_f32_16x16x32_bf16 v[32:35], v[180:183], v[210:213], v[32:35]
	v_mfma_f32_16x16x32_bf16 v[20:23], v[172:175], v[218:221], v[20:23]
	v_mfma_f32_16x16x32_bf16 v[16:19], v[180:183], v[218:221], v[16:19]
	v_mfma_f32_16x16x32_bf16 v[4:7], v[172:175], v[226:229], v[4:7]
	v_mfma_f32_16x16x32_bf16 v[0:3], v[180:183], v[226:229], v[0:3]
	v_mfma_f32_16x16x32_bf16 v[52:55], v[176:179], v[206:209], v[52:55]
	v_mfma_f32_16x16x32_bf16 v[48:51], v[184:187], v[206:209], v[48:51]
	v_mfma_f32_16x16x32_bf16 v[36:39], v[176:179], v[214:217], v[36:39]
	v_mfma_f32_16x16x32_bf16 v[32:35], v[184:187], v[214:217], v[32:35]
	v_mfma_f32_16x16x32_bf16 v[20:23], v[176:179], v[222:225], v[20:23]
	v_mfma_f32_16x16x32_bf16 v[16:19], v[184:187], v[222:225], v[16:19]
	v_mfma_f32_16x16x32_bf16 v[4:7], v[176:179], v[230:233], v[4:7]
	v_mfma_f32_16x16x32_bf16 v[0:3], v[184:187], v[230:233], v[0:3]
	s_setprio 0
.Lgu_half_skip0:
	s_barrier
	s_add_i32 s65, 0, 0x18000
	v_add_u32_e32 v147, s65, v143
	s_add_i32 s66, 0, 0x1c000
	ds_read_b128 v[148:151], v147
	ds_read_b128 v[160:163], v147 offset:1024
	ds_read_b128 v[164:167], v147 offset:2048
	ds_read_b128 v[168:171], v147 offset:3072
	v_add_u32_e32 v147, s66, v143
	ds_read_b128 v[172:175], v147
	ds_read_b128 v[176:179], v147 offset:1024
	ds_read_b128 v[180:183], v147 offset:2048
	ds_read_b128 v[184:187], v147 offset:3072
	s_add_u32 s26, s26, 0x40000
	s_addc_u32 s27, s27, 0
	s_mov_b32 m0, s49
	v_lshl_add_u64 v[198:199], s[26:27], 0, v[130:131]
	ds_read_b128 v[202:205], v146 offset:32768
	ds_read_b128 v[206:209], v146 offset:33792
	ds_read_b128 v[210:213], v146 offset:34816
	ds_read_b128 v[214:217], v146 offset:35840
	ds_read_b128 v[218:221], v146 offset:36864
	ds_read_b128 v[222:225], v146 offset:37888
	ds_read_b128 v[226:229], v146 offset:38912
	ds_read_b128 v[230:233], v146 offset:39936
	global_load_lds_dwordx4 v[198:199], off
	v_lshl_add_u64 v[198:199], s[26:27], 0, v[132:133]
	s_mov_b32 m0, s50
	s_nop 0
	global_load_lds_dwordx4 v[198:199], off
	s_waitcnt vmcnt(8)
	s_waitcnt lgkmcnt(0)
	s_barrier
	s_setprio 1
	s_waitcnt lgkmcnt(0)
	v_mfma_f32_16x16x32_bf16 v[126:129], v[148:151], v[202:205], v[126:129]
	v_mfma_f32_16x16x32_bf16 v[122:125], v[164:167], v[202:205], v[122:125]
	v_mfma_f32_16x16x32_bf16 v[110:113], v[148:151], v[210:213], v[110:113]
	v_mfma_f32_16x16x32_bf16 v[106:109], v[164:167], v[210:213], v[106:109]
	v_mfma_f32_16x16x32_bf16 v[94:97], v[148:151], v[218:221], v[94:97]
	v_mfma_f32_16x16x32_bf16 v[90:93], v[164:167], v[218:221], v[90:93]
	v_mfma_f32_16x16x32_bf16 v[76:79], v[148:151], v[226:229], v[76:79]
	v_mfma_f32_16x16x32_bf16 v[72:75], v[164:167], v[226:229], v[72:75]
	v_mfma_f32_16x16x32_bf16 v[126:129], v[160:163], v[206:209], v[126:129]
	v_mfma_f32_16x16x32_bf16 v[122:125], v[168:171], v[206:209], v[122:125]
	v_mfma_f32_16x16x32_bf16 v[110:113], v[160:163], v[214:217], v[110:113]
	v_mfma_f32_16x16x32_bf16 v[106:109], v[168:171], v[214:217], v[106:109]
	v_mfma_f32_16x16x32_bf16 v[94:97], v[160:163], v[222:225], v[94:97]
	v_mfma_f32_16x16x32_bf16 v[90:93], v[168:171], v[222:225], v[90:93]
	v_mfma_f32_16x16x32_bf16 v[76:79], v[160:163], v[230:233], v[76:79]
	v_mfma_f32_16x16x32_bf16 v[72:75], v[168:171], v[230:233], v[72:75]
	s_setprio 0
	s_setprio 1
	v_mfma_f32_16x16x32_bf16 v[118:121], v[172:175], v[202:205], v[118:121]
	v_mfma_f32_16x16x32_bf16 v[114:117], v[180:183], v[202:205], v[114:117]
	v_mfma_f32_16x16x32_bf16 v[102:105], v[172:175], v[210:213], v[102:105]
	v_mfma_f32_16x16x32_bf16 v[98:101], v[180:183], v[210:213], v[98:101]
	v_mfma_f32_16x16x32_bf16 v[86:89], v[172:175], v[218:221], v[86:89]
	v_mfma_f32_16x16x32_bf16 v[82:85], v[180:183], v[218:221], v[82:85]
	v_mfma_f32_16x16x32_bf16 v[68:71], v[172:175], v[226:229], v[68:71]
	v_mfma_f32_16x16x32_bf16 v[64:67], v[180:183], v[226:229], v[64:67]
	v_mfma_f32_16x16x32_bf16 v[118:121], v[176:179], v[206:209], v[118:121]
	v_mfma_f32_16x16x32_bf16 v[114:117], v[184:187], v[206:209], v[114:117]
	v_mfma_f32_16x16x32_bf16 v[102:105], v[176:179], v[214:217], v[102:105]
	v_mfma_f32_16x16x32_bf16 v[98:101], v[184:187], v[214:217], v[98:101]
	v_mfma_f32_16x16x32_bf16 v[86:89], v[176:179], v[222:225], v[86:89]
	v_mfma_f32_16x16x32_bf16 v[82:85], v[184:187], v[222:225], v[82:85]
	v_mfma_f32_16x16x32_bf16 v[68:71], v[176:179], v[230:233], v[68:71]
	v_mfma_f32_16x16x32_bf16 v[64:67], v[184:187], v[230:233], v[64:67]
	s_setprio 0
	s_barrier
; #define PG8_STAGE(bufoff, gbase, voff) do { _Pragma("unroll") for (int _i = 0; _i < 2; ++_i) \
;         __builtin_amdgcn_global_load_lds((const unsigned*)((const char*)(gbase) + (voff)[_i]), (PG8_LAS unsigned*)(lds + (bufoff) + ldsw + _i * 8192), 16, 0, 0); } while (0)
; #define PG8_LDA(dst, b, h) do { _Pragma("unroll") for (int m = 0; m < 4; ++m) _Pragma("unroll") for (int k = 0; k < 2; ++k) dst[m][k] = *(const PG8_LAS bf16x8*)(lds + PG8_SA(b, h) + aoff + m * 2048 + k * 1024); } while (0)
; #define PG8_MMA(ai, bj, At, Bt) do { __builtin_amdgcn_s_setprio(1); _Pragma("unroll") for (int m = 0; m < 4; ++m) _Pragma("unroll") for (int n = 0; n < 2; ++n) _Pragma("unroll") for (int k = 0; k < 2; ++k) \
;         acc[ai][bj][m][n] = __builtin_amdgcn_mfma_f32_16x16x32_bf16(Bt[n][k], At[m][k], acc[ai][bj][m][n], 0, 0, 0); __builtin_amdgcn_s_setprio(0); } while (0)
; #define PG8_WAIT_V(n) asm volatile("s_waitcnt vmcnt(" #n ")" ::: "memory")
; #define PG8_WAIT_L(n) asm volatile("s_waitcnt lgkmcnt(" #n ")" ::: "memory")
; #define PG8_BAR __builtin_amdgcn_s_barrier()
; #define PG8_SCHED __builtin_amdgcn_sched_barrier(0)
; template <class Epi, class Sched, bool ALIGN_EPI = false, bool SP2 = false, bool HALFM = false>
; __device__ __forceinline__ void gemm_phase(PG8_LAS unsigned char* lds, const Gemm g, const Sched& S, const Epi& E) {
;     ...
;         for (int t = 0; t < nt; t += 2) {
;     ...
;             if constexpr (!HALFM) PG8_LDA(At, 1, 1); PG8_STAGE(PG8_SB(1, 0), b3, voffB); PG8_STAGE(PG8_SB(1, 1), b3 + hstep, voffB); PG8_STAGE(PG8_SA(1, 0), a3, voffA);
;             PG8_WAIT_V(8); PG8_WAIT_L(0); PG8_BAR; if constexpr (!HALFM) { PG8_MMA(1, 0, At, B0); PG8_MMA(1, 1, At, B1); } PG8_BAR; PG8_SCHED;
	s_add_i32 s26, s65, s46
	v_lshl_add_u64 v[140:141], v[140:141], 0, s[82:83]
	s_mov_b32 m0, s26
	ds_read_b128 v[202:205], v146 offset:49152
	ds_read_b128 v[206:209], v146 offset:50176
	ds_read_b128 v[210:213], v146 offset:51200
	ds_read_b128 v[214:217], v146 offset:52224
	ds_read_b128 v[218:221], v146 offset:53248
	ds_read_b128 v[222:225], v146 offset:54272
	ds_read_b128 v[226:229], v146 offset:55296
	ds_read_b128 v[230:233], v146 offset:56320
	global_load_lds_dwordx4 v[140:141], off
	s_add_i32 m0, s26, 0x2000
	s_add_u32 s24, s24, 0x40080
	v_lshl_add_u64 v[140:141], v[152:153], 0, s[82:83]
	s_addc_u32 s25, s25, 0
	s_add_i32 s26, s66, s46
	global_load_lds_dwordx4 v[140:141], off
	v_lshl_add_u64 v[140:141], s[24:25], 0, v[80:81]
	s_mov_b32 m0, s26
	s_nop 0
	global_load_lds_dwordx4 v[140:141], off
	v_lshl_add_u64 v[140:141], s[24:25], 0, v[134:135]
	s_add_i32 m0, s26, 0x2000
	s_nop 0
	global_load_lds_dwordx4 v[140:141], off
	v_lshl_add_u64 v[140:141], v[188:189], 0, s[82:83]
	s_mov_b32 m0, s51
	s_nop 0
	global_load_lds_dwordx4 v[140:141], off
	v_lshl_add_u64 v[140:141], v[196:197], 0, s[82:83]
	s_mov_b32 m0, s52
	s_nop 0
	global_load_lds_dwordx4 v[140:141], off
	s_waitcnt vmcnt(8)
	s_waitcnt lgkmcnt(0)
	s_barrier
	s_cmp_lg_u32 s99, 0
	s_cbranch_scc1 .Lgu_half_skip1
	s_setprio 1
	s_waitcnt lgkmcnt(0)
	v_mfma_f32_16x16x32_bf16 v[60:63], v[148:151], v[202:205], v[60:63]
	v_mfma_f32_16x16x32_bf16 v[56:59], v[164:167], v[202:205], v[56:59]
	v_mfma_f32_16x16x32_bf16 v[44:47], v[148:151], v[210:213], v[44:47]
	v_mfma_f32_16x16x32_bf16 v[40:43], v[164:167], v[210:213], v[40:43]
	v_mfma_f32_16x16x32_bf16 v[28:31], v[148:151], v[218:221], v[28:31]
	v_mfma_f32_16x16x32_bf16 v[24:27], v[164:167], v[218:221], v[24:27]
	v_mfma_f32_16x16x32_bf16 v[12:15], v[148:151], v[226:229], v[12:15]
	v_mfma_f32_16x16x32_bf16 v[8:11], v[164:167], v[226:229], v[8:11]
	v_mfma_f32_16x16x32_bf16 v[60:63], v[160:163], v[206:209], v[60:63]
	v_mfma_f32_16x16x32_bf16 v[56:59], v[168:171], v[206:209], v[56:59]
	v_mfma_f32_16x16x32_bf16 v[44:47], v[160:163], v[214:217], v[44:47]
	v_mfma_f32_16x16x32_bf16 v[40:43], v[168:171], v[214:217], v[40:43]
	v_mfma_f32_16x16x32_bf16 v[28:31], v[160:163], v[222:225], v[28:31]
	v_mfma_f32_16x16x32_bf16 v[24:27], v[168:171], v[222:225], v[24:27]
	v_mfma_f32_16x16x32_bf16 v[12:15], v[160:163], v[230:233], v[12:15]
	v_mfma_f32_16x16x32_bf16 v[8:11], v[168:171], v[230:233], v[8:11]
	s_setprio 0
	s_setprio 1
	v_mfma_f32_16x16x32_bf16 v[52:55], v[172:175], v[202:205], v[52:55]
	v_mfma_f32_16x16x32_bf16 v[48:51], v[180:183], v[202:205], v[48:51]
	v_mfma_f32_16x16x32_bf16 v[36:39], v[172:175], v[210:213], v[36:39]
	v_mfma_f32_16x16x32_bf16 v[32:35], v[180:183], v[210:213], v[32:35]
	v_mfma_f32_16x16x32_bf16 v[20:23], v[172:175], v[218:221], v[20:23]
	v_mfma_f32_16x16x32_bf16 v[16:19], v[180:183], v[218:221], v[16:19]
	v_mfma_f32_16x16x32_bf16 v[4:7], v[172:175], v[226:229], v[4:7]
	v_mfma_f32_16x16x32_bf16 v[0:3], v[180:183], v[226:229], v[0:3]
	v_mfma_f32_16x16x32_bf16 v[52:55], v[176:179], v[206:209], v[52:55]
	v_mfma_f32_16x16x32_bf16 v[48:51], v[184:187], v[206:209], v[48:51]
	v_mfma_f32_16x16x32_bf16 v[36:39], v[176:179], v[214:217], v[36:39]
	v_mfma_f32_16x16x32_bf16 v[32:35], v[184:187], v[214:217], v[32:35]
	v_mfma_f32_16x16x32_bf16 v[20:23], v[176:179], v[222:225], v[20:23]
	v_mfma_f32_16x16x32_bf16 v[16:19], v[184:187], v[222:225], v[16:19]
	v_mfma_f32_16x16x32_bf16 v[4:7], v[176:179], v[230:233], v[4:7]
	v_mfma_f32_16x16x32_bf16 v[0:3], v[184:187], v[230:233], v[0:3]
	s_setprio 0
.Lgu_half_skip1:
	s_barrier
	s_add_i32 s64, s64, 2
	s_add_u32 s22, s22, 0x100
	s_addc_u32 s23, s23, 0
	s_add_u32 s62, s62, 0x100
	s_addc_u32 s63, s63, 0
	s_cmp_gt_u32 s64, 13
	s_cbranch_scc1 .LBB0_183

; __device__ __forceinline__ unsigned cvt_pk_bf16(float lo, float hi) { unsigned r; asm volatile("v_cvt_pk_bf16_f32 %0, %1, %2" : "=v"(r) : "v"(lo), "v"(hi)); return r; }
;     __device__ __forceinline__ void operator()(const f32x4 (&acc)[2][2][4][2], const Unit& u, int wr, int wc, int fr, int fq) const {
;         const int row0 = u.pm * BM + u.roff + wr * 64 + fr, col0 = u.pn * HALF + wc * 32 + 8 * fq;
; #pragma unroll
;         for (int ai = 0; ai < NAI; ++ai)
; #pragma unroll
;             for (int m = 0; m < 4; ++m) {
;                 const int row = row0 + ai * HALF + m * 16; const float ri = tab[u.par * 256 + ai * HALF + wr * 64 + m * 16 + fr];
;                 const f32x4 g0 = acc[ai][0][m][0] * ri, g1 = acc[ai][0][m][1] * ri, u0 = acc[ai][1][m][0] * ri, u1 = acc[ai][1][m][1] * ri;
;                 u32x4 w;
;                 w.x = pg8::cvt_pk_bf16(silu_mul(g0[0], u0[0]), silu_mul(g0[1], u0[1])); w.y = pg8::cvt_pk_bf16(silu_mul(g0[2], u0[2]), silu_mul(g0[3], u0[3]));
;                 w.z = pg8::cvt_pk_bf16(silu_mul(g1[0], u1[0]), silu_mul(g1[1], u1[1])); w.w = pg8::cvt_pk_bf16(silu_mul(g1[2], u1[2]), silu_mul(g1[3], u1[3]));
;                 *(u32x4*)(O + (size_t)row * DFF + col0) = w;
;                 if (m & 1) asm volatile("" ::: "memory");
;             }
.LBB0_185:
	v_lshl_add_u32 v147, s55, 10, v145
	v_lshl_add_u32 v147, s101, 2, v147
	ds_read_b32 v150, v147
	v_readlane_b32 s18, v254, 11
	v_lshl_or_b32 v140, s56, 7, v144
	v_readlane_b32 s19, v254, 12
	v_lshl_add_u32 v148, s57, 8, v142
	v_add_u32_e32 v148, s101, v148
	s_waitcnt lgkmcnt(0)
	v_pk_mul_f32 v[126:127], v[126:127], v[150:151] op_sel_hi:[1,0]
	v_pk_mul_f32 v[118:119], v[118:119], v[150:151] op_sel_hi:[1,0]
	v_mul_f32_e32 v149, 0xbfb8aa3b, v126
	v_exp_f32_e32 v149, v149
	v_pk_mul_f32 v[128:129], v[128:129], v[150:151] op_sel_hi:[1,0]
	v_pk_mul_f32 v[120:121], v[120:121], v[150:151] op_sel_hi:[1,0]
	v_pk_mul_f32 v[122:123], v[122:123], v[150:151] op_sel_hi:[1,0]
	v_add_f32_e32 v149, 1.0, v149
	v_rcp_f32_e32 v149, v149
	v_pk_mul_f32 v[114:115], v[114:115], v[150:151] op_sel_hi:[1,0]
	v_pk_mul_f32 v[124:125], v[124:125], v[150:151] op_sel_hi:[1,0]
	v_pk_mul_f32 v[116:117], v[116:117], v[150:151] op_sel_hi:[1,0]
	v_mul_f32_e32 v126, v126, v149
	v_mul_f32_e32 v118, v118, v126
	v_mul_f32_e32 v126, 0xbfb8aa3b, v127
	v_exp_f32_e32 v126, v126
	v_ashrrev_i32_e32 v141, 31, v140
	s_andn2_b64 vcc, exec, s[16:17]
	v_add_f32_e32 v126, 1.0, v126
	v_rcp_f32_e32 v126, v126
	s_nop 0
	v_mul_f32_e32 v126, v127, v126
	v_mul_f32_e32 v119, v119, v126
	v_cvt_pk_bf16_f32 v118, v118, v119
	v_mul_f32_e32 v119, 0xbfb8aa3b, v128
	v_exp_f32_e32 v119, v119
	s_nop 0
	v_add_f32_e32 v119, 1.0, v119
	v_rcp_f32_e32 v119, v119
	s_nop 0
	v_mul_f32_e32 v119, v128, v119
	v_mul_f32_e32 v119, v120, v119
	v_mul_f32_e32 v120, 0xbfb8aa3b, v129
	v_exp_f32_e32 v120, v120
	s_nop 0
	v_add_f32_e32 v120, 1.0, v120
	v_rcp_f32_e32 v120, v120
	s_nop 0
	v_mul_f32_e32 v120, v129, v120
	v_mul_f32_e32 v120, v121, v120
	v_cvt_pk_bf16_f32 v119, v119, v120
	v_mul_f32_e32 v120, 0xbfb8aa3b, v122
	v_exp_f32_e32 v120, v120
	s_nop 0
	v_add_f32_e32 v120, 1.0, v120
	v_rcp_f32_e32 v120, v120
	s_nop 0
	v_mul_f32_e32 v120, v122, v120
	v_mul_f32_e32 v114, v114, v120
	v_mul_f32_e32 v120, 0xbfb8aa3b, v123
	v_exp_f32_e32 v120, v120
	s_nop 0
	v_add_f32_e32 v120, 1.0, v120
	v_rcp_f32_e32 v120, v120
	s_nop 0
	v_mul_f32_e32 v120, v123, v120
	v_mul_f32_e32 v115, v115, v120
	v_cvt_pk_bf16_f32 v120, v114, v115
	v_mul_f32_e32 v114, 0xbfb8aa3b, v124
	v_mul_f32_e32 v115, 0xbfb8aa3b, v125
	v_exp_f32_e32 v114, v114
	v_exp_f32_e32 v115, v115
	v_add_f32_e32 v114, 1.0, v114
	v_add_f32_e32 v115, 1.0, v115
	v_rcp_f32_e32 v114, v114
	v_rcp_f32_e32 v115, v115
	v_mul_f32_e32 v114, v124, v114
	v_mul_f32_e32 v115, v125, v115
	v_mul_f32_e32 v114, v116, v114
	v_mul_f32_e32 v115, v117, v115
	v_cvt_pk_bf16_f32 v121, v114, v115
	v_mov_b64_e32 v[114:115], s[18:19]
	v_mad_i64_i32 v[122:123], s[18:19], v148, s41, v[114:115]
	v_lshlrev_b64 v[116:117], 1, v[140:141]
	v_lshl_add_u64 v[122:123], v[122:123], 0, v[116:117]
	global_store_dwordx4 v[122:123], v[118:121], off
	ds_read_b32 v118, v147 offset:64
	s_nop 0
	v_or_b32_e32 v119, 16, v148
	s_waitcnt lgkmcnt(0)
	v_pk_mul_f32 v[110:111], v[110:111], v[118:119] op_sel_hi:[1,0]
	v_pk_mul_f32 v[120:121], v[100:101], v[118:119] op_sel_hi:[1,0]
	v_pk_mul_f32 v[100:101], v[98:99], v[118:119] op_sel_hi:[1,0]
	v_mul_f32_e32 v98, 0xbfb8aa3b, v110
	v_mul_f32_e32 v99, 0xbfb8aa3b, v111
	v_exp_f32_e32 v98, v98
	v_exp_f32_e32 v99, v99
	v_pk_mul_f32 v[102:103], v[102:103], v[118:119] op_sel_hi:[1,0]
	v_pk_mul_f32 v[112:113], v[112:113], v[118:119] op_sel_hi:[1,0]
	v_add_f32_e32 v98, 1.0, v98
	v_add_f32_e32 v99, 1.0, v99
	v_rcp_f32_e32 v98, v98
	v_rcp_f32_e32 v99, v99
	v_pk_mul_f32 v[104:105], v[104:105], v[118:119] op_sel_hi:[1,0]
	v_pk_mul_f32 v[106:107], v[106:107], v[118:119] op_sel_hi:[1,0]
	v_mul_f32_e32 v98, v110, v98
	v_mul_f32_e32 v99, v111, v99
	v_mul_f32_e32 v98, v102, v98
	v_mul_f32_e32 v99, v103, v99
	v_cvt_pk_bf16_f32 v98, v98, v99
	v_mul_f32_e32 v99, 0xbfb8aa3b, v112
	v_mul_f32_e32 v102, 0xbfb8aa3b, v113
	v_exp_f32_e32 v99, v99
	v_exp_f32_e32 v102, v102
	v_pk_mul_f32 v[108:109], v[108:109], v[118:119] op_sel_hi:[1,0]
	v_add_f32_e32 v99, 1.0, v99
	v_add_f32_e32 v102, 1.0, v102
	v_rcp_f32_e32 v99, v99
	v_rcp_f32_e32 v102, v102
	v_mul_f32_e32 v99, v112, v99
	v_mul_f32_e32 v102, v113, v102
	v_mul_f32_e32 v99, v104, v99
	v_mul_f32_e32 v102, v105, v102
	v_cvt_pk_bf16_f32 v99, v99, v102
	v_mul_f32_e32 v102, 0xbfb8aa3b, v106
	v_exp_f32_e32 v102, v102
	s_nop 0
	v_add_f32_e32 v102, 1.0, v102
	v_rcp_f32_e32 v102, v102
	s_nop 0
	v_mul_f32_e32 v102, v106, v102
	v_mul_f32_e32 v100, v100, v102
	v_mul_f32_e32 v102, 0xbfb8aa3b, v107
	v_exp_f32_e32 v102, v102
	s_nop 0
	v_add_f32_e32 v102, 1.0, v102
	v_rcp_f32_e32 v102, v102
	s_nop 0
	v_mul_f32_e32 v102, v107, v102
	v_mul_f32_e32 v101, v101, v102
	v_cvt_pk_bf16_f32 v100, v100, v101
	v_mul_f32_e32 v101, 0xbfb8aa3b, v108
	v_mul_f32_e32 v102, 0xbfb8aa3b, v109
	v_exp_f32_e32 v101, v101
	v_exp_f32_e32 v102, v102
	v_add_f32_e32 v101, 1.0, v101
	v_add_f32_e32 v102, 1.0, v102
	v_rcp_f32_e32 v101, v101
	v_rcp_f32_e32 v102, v102
	v_mul_f32_e32 v101, v108, v101
	v_mul_f32_e32 v102, v109, v102
	v_mul_f32_e32 v101, v120, v101
	v_mul_f32_e32 v102, v121, v102
	v_cvt_pk_bf16_f32 v101, v101, v102
	v_mad_i64_i32 v[102:103], s[18:19], v119, s41, v[114:115]
	v_lshl_add_u64 v[102:103], v[102:103], 0, v[116:117]
	global_store_dwordx4 v[102:103], v[98:101], off
	ds_read_b32 v98, v147 offset:128
	s_nop 0
	v_or_b32_e32 v99, 32, v148
	s_waitcnt lgkmcnt(0)
; __device__ __forceinline__ unsigned cvt_pk_bf16(float lo, float hi) { unsigned r; asm volatile("v_cvt_pk_bf16_f32 %0, %1, %2" : "=v"(r) : "v"(lo), "v"(hi)); return r; }
;     __device__ __forceinline__ void operator()(const f32x4 (&acc)[2][2][4][2], const Unit& u, int wr, int wc, int fr, int fq) const {
;         const int row0 = u.pm * BM + u.roff + wr * 64 + fr, col0 = u.pn * HALF + wc * 32 + 8 * fq;
; #pragma unroll
;         for (int ai = 0; ai < NAI; ++ai)
; #pragma unroll
;             for (int m = 0; m < 4; ++m) {
;                 const int row = row0 + ai * HALF + m * 16; const float ri = tab[u.par * 256 + ai * HALF + wr * 64 + m * 16 + fr];
;                 const f32x4 g0 = acc[ai][0][m][0] * ri, g1 = acc[ai][0][m][1] * ri, u0 = acc[ai][1][m][0] * ri, u1 = acc[ai][1][m][1] * ri;
;                 u32x4 w;
;                 w.x = pg8::cvt_pk_bf16(silu_mul(g0[0], u0[0]), silu_mul(g0[1], u0[1])); w.y = pg8::cvt_pk_bf16(silu_mul(g0[2], u0[2]), silu_mul(g0[3], u0[3]));
;                 w.z = pg8::cvt_pk_bf16(silu_mul(g1[0], u1[0]), silu_mul(g1[1], u1[1])); w.w = pg8::cvt_pk_bf16(silu_mul(g1[2], u1[2]), silu_mul(g1[3], u1[3]));
;                 *(u32x4*)(O + (size_t)row * DFF + col0) = w;
;                 if (m & 1) asm volatile("" ::: "memory");
;             }
	v_pk_mul_f32 v[94:95], v[94:95], v[98:99] op_sel_hi:[1,0]
	v_pk_mul_f32 v[100:101], v[84:85], v[98:99] op_sel_hi:[1,0]
	v_pk_mul_f32 v[84:85], v[82:83], v[98:99] op_sel_hi:[1,0]
	v_mul_f32_e32 v82, 0xbfb8aa3b, v94
	v_mul_f32_e32 v83, 0xbfb8aa3b, v95
	v_exp_f32_e32 v82, v82
	v_exp_f32_e32 v83, v83
	v_pk_mul_f32 v[86:87], v[86:87], v[98:99] op_sel_hi:[1,0]
	v_pk_mul_f32 v[96:97], v[96:97], v[98:99] op_sel_hi:[1,0]
	v_add_f32_e32 v82, 1.0, v82
	v_add_f32_e32 v83, 1.0, v83
	v_rcp_f32_e32 v82, v82
	v_rcp_f32_e32 v83, v83
	v_pk_mul_f32 v[88:89], v[88:89], v[98:99] op_sel_hi:[1,0]
	v_pk_mul_f32 v[90:91], v[90:91], v[98:99] op_sel_hi:[1,0]
	v_mul_f32_e32 v82, v94, v82
	v_mul_f32_e32 v83, v95, v83
	v_mul_f32_e32 v82, v86, v82
	v_mul_f32_e32 v83, v87, v83
	v_cvt_pk_bf16_f32 v82, v82, v83
	v_mul_f32_e32 v83, 0xbfb8aa3b, v96
	v_mul_f32_e32 v86, 0xbfb8aa3b, v97
	v_exp_f32_e32 v83, v83
	v_exp_f32_e32 v86, v86
	v_pk_mul_f32 v[92:93], v[92:93], v[98:99] op_sel_hi:[1,0]
	v_add_f32_e32 v83, 1.0, v83
	v_add_f32_e32 v86, 1.0, v86
	v_rcp_f32_e32 v83, v83
	v_rcp_f32_e32 v86, v86
	v_mul_f32_e32 v83, v96, v83
	v_mul_f32_e32 v86, v97, v86
	v_mul_f32_e32 v83, v88, v83
	v_mul_f32_e32 v86, v89, v86
	v_cvt_pk_bf16_f32 v83, v83, v86
	v_mul_f32_e32 v86, 0xbfb8aa3b, v90
	v_exp_f32_e32 v86, v86
	s_nop 0
	v_add_f32_e32 v86, 1.0, v86
	v_rcp_f32_e32 v86, v86
	s_nop 0
	v_mul_f32_e32 v86, v90, v86
	v_mul_f32_e32 v84, v84, v86
	v_mul_f32_e32 v86, 0xbfb8aa3b, v91
	v_exp_f32_e32 v86, v86
	s_nop 0
	v_add_f32_e32 v86, 1.0, v86
	v_rcp_f32_e32 v86, v86
	s_nop 0
	v_mul_f32_e32 v86, v91, v86
	v_mul_f32_e32 v85, v85, v86
	v_cvt_pk_bf16_f32 v84, v84, v85
	v_mul_f32_e32 v85, 0xbfb8aa3b, v92
	v_mul_f32_e32 v86, 0xbfb8aa3b, v93
	v_exp_f32_e32 v85, v85
	v_exp_f32_e32 v86, v86
	v_add_f32_e32 v85, 1.0, v85
	v_add_f32_e32 v86, 1.0, v86
	v_rcp_f32_e32 v85, v85
	v_rcp_f32_e32 v86, v86
	v_mul_f32_e32 v85, v92, v85
	v_mul_f32_e32 v86, v93, v86
	v_mul_f32_e32 v85, v100, v85
	v_mul_f32_e32 v86, v101, v86
	v_cvt_pk_bf16_f32 v85, v85, v86
	v_mad_i64_i32 v[86:87], s[18:19], v99, s41, v[114:115]
	v_lshl_add_u64 v[86:87], v[86:87], 0, v[116:117]
	global_store_dwordx4 v[86:87], v[82:85], off
	ds_read_b32 v82, v147 offset:192
	s_nop 0
	v_or_b32_e32 v83, 48, v148
	s_waitcnt lgkmcnt(0)
	v_pk_mul_f32 v[76:77], v[76:77], v[82:83] op_sel_hi:[1,0]
	v_pk_mul_f32 v[84:85], v[66:67], v[82:83] op_sel_hi:[1,0]
	v_pk_mul_f32 v[66:67], v[64:65], v[82:83] op_sel_hi:[1,0]
	v_mul_f32_e32 v64, 0xbfb8aa3b, v76
	v_mul_f32_e32 v65, 0xbfb8aa3b, v77
	v_exp_f32_e32 v64, v64
	v_exp_f32_e32 v65, v65
	v_pk_mul_f32 v[68:69], v[68:69], v[82:83] op_sel_hi:[1,0]
	v_pk_mul_f32 v[78:79], v[78:79], v[82:83] op_sel_hi:[1,0]
	v_add_f32_e32 v64, 1.0, v64
	v_add_f32_e32 v65, 1.0, v65
	v_rcp_f32_e32 v64, v64
	v_rcp_f32_e32 v65, v65
	v_pk_mul_f32 v[70:71], v[70:71], v[82:83] op_sel_hi:[1,0]
	v_pk_mul_f32 v[72:73], v[72:73], v[82:83] op_sel_hi:[1,0]
	v_mul_f32_e32 v64, v76, v64
	v_mul_f32_e32 v65, v77, v65
	v_mul_f32_e32 v64, v68, v64
	v_mul_f32_e32 v65, v69, v65
	v_cvt_pk_bf16_f32 v64, v64, v65
	v_mul_f32_e32 v65, 0xbfb8aa3b, v78
	v_mul_f32_e32 v68, 0xbfb8aa3b, v79
	v_exp_f32_e32 v65, v65
	v_exp_f32_e32 v68, v68
	v_pk_mul_f32 v[74:75], v[74:75], v[82:83] op_sel_hi:[1,0]
	v_add_f32_e32 v65, 1.0, v65
	v_add_f32_e32 v68, 1.0, v68
	v_rcp_f32_e32 v65, v65
	v_rcp_f32_e32 v68, v68
	v_mul_f32_e32 v65, v78, v65
	v_mul_f32_e32 v68, v79, v68
	v_mul_f32_e32 v65, v70, v65
	v_mul_f32_e32 v68, v71, v68
	v_cvt_pk_bf16_f32 v65, v65, v68
	v_mul_f32_e32 v68, 0xbfb8aa3b, v72
	v_exp_f32_e32 v68, v68
	s_nop 0
	v_add_f32_e32 v68, 1.0, v68
	v_rcp_f32_e32 v68, v68
	s_nop 0
	v_mul_f32_e32 v68, v72, v68
	v_mul_f32_e32 v66, v66, v68
	v_mul_f32_e32 v68, 0xbfb8aa3b, v73
	v_exp_f32_e32 v68, v68
	s_nop 0
	v_add_f32_e32 v68, 1.0, v68
	v_rcp_f32_e32 v68, v68
	s_nop 0
	v_mul_f32_e32 v68, v73, v68
	v_mul_f32_e32 v67, v67, v68
	v_cvt_pk_bf16_f32 v66, v66, v67
	v_mul_f32_e32 v67, 0xbfb8aa3b, v74
	v_mul_f32_e32 v68, 0xbfb8aa3b, v75
	v_exp_f32_e32 v67, v67
	v_exp_f32_e32 v68, v68
	v_add_f32_e32 v67, 1.0, v67
	v_add_f32_e32 v68, 1.0, v68
	v_rcp_f32_e32 v67, v67
	v_rcp_f32_e32 v68, v68
	v_mul_f32_e32 v67, v74, v67
	v_mul_f32_e32 v68, v75, v68
	v_mul_f32_e32 v67, v84, v67
	v_mul_f32_e32 v68, v85, v68
	v_cvt_pk_bf16_f32 v67, v67, v68
	v_mad_i64_i32 v[68:69], s[18:19], v83, s41, v[114:115]
	v_lshl_add_u64 v[68:69], v[68:69], 0, v[116:117]
	global_store_dwordx4 v[68:69], v[64:67], off
	s_cmp_lg_u32 s99, 0
	s_cbranch_scc1 .Lgu_epi_half_end
; __device__ __forceinline__ unsigned cvt_pk_bf16(float lo, float hi) { unsigned r; asm volatile("v_cvt_pk_bf16_f32 %0, %1, %2" : "=v"(r) : "v"(lo), "v"(hi)); return r; }
;     __device__ __forceinline__ void operator()(const f32x4 (&acc)[2][2][4][2], const Unit& u, int wr, int wc, int fr, int fq) const {
;         const int row0 = u.pm * BM + u.roff + wr * 64 + fr, col0 = u.pn * HALF + wc * 32 + 8 * fq;
; #pragma unroll
;         for (int ai = 0; ai < NAI; ++ai)
; #pragma unroll
;             for (int m = 0; m < 4; ++m) {
;                 const int row = row0 + ai * HALF + m * 16; const float ri = tab[u.par * 256 + ai * HALF + wr * 64 + m * 16 + fr];
;                 const f32x4 g0 = acc[ai][0][m][0] * ri, g1 = acc[ai][0][m][1] * ri, u0 = acc[ai][1][m][0] * ri, u1 = acc[ai][1][m][1] * ri;
;                 u32x4 w;
;                 w.x = pg8::cvt_pk_bf16(silu_mul(g0[0], u0[0]), silu_mul(g0[1], u0[1])); w.y = pg8::cvt_pk_bf16(silu_mul(g0[2], u0[2]), silu_mul(g0[3], u0[3]));
;                 w.z = pg8::cvt_pk_bf16(silu_mul(g1[0], u1[0]), silu_mul(g1[1], u1[1])); w.w = pg8::cvt_pk_bf16(silu_mul(g1[2], u1[2]), silu_mul(g1[3], u1[3]));
;                 *(u32x4*)(O + (size_t)row * DFF + col0) = w;
;                 if (m & 1) asm volatile("" ::: "memory");
;             }
	ds_read_b32 v64, v147 offset:512
	s_nop 0
	v_add_u32_e32 v65, 0x80, v148
	s_waitcnt lgkmcnt(0)
	v_pk_mul_f32 v[60:61], v[60:61], v[64:65] op_sel_hi:[1,0]
	v_pk_mul_f32 v[66:67], v[50:51], v[64:65] op_sel_hi:[1,0]
	v_pk_mul_f32 v[50:51], v[48:49], v[64:65] op_sel_hi:[1,0]
	v_mul_f32_e32 v48, 0xbfb8aa3b, v60
	v_mul_f32_e32 v49, 0xbfb8aa3b, v61
	v_exp_f32_e32 v48, v48
	v_exp_f32_e32 v49, v49
	v_pk_mul_f32 v[52:53], v[52:53], v[64:65] op_sel_hi:[1,0]
	v_pk_mul_f32 v[62:63], v[62:63], v[64:65] op_sel_hi:[1,0]
	v_add_f32_e32 v48, 1.0, v48
	v_add_f32_e32 v49, 1.0, v49
	v_rcp_f32_e32 v48, v48
	v_rcp_f32_e32 v49, v49
	v_pk_mul_f32 v[54:55], v[54:55], v[64:65] op_sel_hi:[1,0]
	v_pk_mul_f32 v[56:57], v[56:57], v[64:65] op_sel_hi:[1,0]
	v_mul_f32_e32 v48, v60, v48
	v_mul_f32_e32 v49, v61, v49
	v_mul_f32_e32 v48, v52, v48
	v_mul_f32_e32 v49, v53, v49
	v_cvt_pk_bf16_f32 v48, v48, v49
	v_mul_f32_e32 v49, 0xbfb8aa3b, v62
	v_mul_f32_e32 v52, 0xbfb8aa3b, v63
	v_exp_f32_e32 v49, v49
	v_exp_f32_e32 v52, v52
	v_pk_mul_f32 v[58:59], v[58:59], v[64:65] op_sel_hi:[1,0]
	v_add_f32_e32 v49, 1.0, v49
	v_add_f32_e32 v52, 1.0, v52
	v_rcp_f32_e32 v49, v49
	v_rcp_f32_e32 v52, v52
	v_mul_f32_e32 v49, v62, v49
	v_mul_f32_e32 v52, v63, v52
	v_mul_f32_e32 v49, v54, v49
	v_mul_f32_e32 v52, v55, v52
	v_cvt_pk_bf16_f32 v49, v49, v52
	v_mul_f32_e32 v52, 0xbfb8aa3b, v56
	v_exp_f32_e32 v52, v52
	s_nop 0
	v_add_f32_e32 v52, 1.0, v52
	v_rcp_f32_e32 v52, v52
	s_nop 0
	v_mul_f32_e32 v52, v56, v52
	v_mul_f32_e32 v50, v50, v52
	v_mul_f32_e32 v52, 0xbfb8aa3b, v57
	v_exp_f32_e32 v52, v52
	s_nop 0
	v_add_f32_e32 v52, 1.0, v52
	v_rcp_f32_e32 v52, v52
	s_nop 0
	v_mul_f32_e32 v52, v57, v52
	v_mul_f32_e32 v51, v51, v52
	v_cvt_pk_bf16_f32 v50, v50, v51
	v_mul_f32_e32 v51, 0xbfb8aa3b, v58
	v_mul_f32_e32 v52, 0xbfb8aa3b, v59
	v_exp_f32_e32 v51, v51
	v_exp_f32_e32 v52, v52
	v_add_f32_e32 v51, 1.0, v51
	v_add_f32_e32 v52, 1.0, v52
	v_rcp_f32_e32 v51, v51
	v_rcp_f32_e32 v52, v52
	v_mul_f32_e32 v51, v58, v51
	v_mul_f32_e32 v52, v59, v52
	v_mul_f32_e32 v51, v66, v51
	v_mul_f32_e32 v52, v67, v52
	v_cvt_pk_bf16_f32 v51, v51, v52
	v_mad_i64_i32 v[52:53], s[18:19], v65, s41, v[114:115]
	v_lshl_add_u64 v[52:53], v[52:53], 0, v[116:117]
	global_store_dwordx4 v[52:53], v[48:51], off
	ds_read_b32 v48, v147 offset:576
	s_nop 0
	v_add_u32_e32 v49, 0x90, v148
	s_waitcnt lgkmcnt(0)
	v_pk_mul_f32 v[44:45], v[44:45], v[48:49] op_sel_hi:[1,0]
	v_pk_mul_f32 v[50:51], v[34:35], v[48:49] op_sel_hi:[1,0]
	v_pk_mul_f32 v[34:35], v[32:33], v[48:49] op_sel_hi:[1,0]
	v_mul_f32_e32 v32, 0xbfb8aa3b, v44
	v_mul_f32_e32 v33, 0xbfb8aa3b, v45
	v_exp_f32_e32 v32, v32
	v_exp_f32_e32 v33, v33
	v_pk_mul_f32 v[36:37], v[36:37], v[48:49] op_sel_hi:[1,0]
	v_pk_mul_f32 v[46:47], v[46:47], v[48:49] op_sel_hi:[1,0]
	v_add_f32_e32 v32, 1.0, v32
	v_add_f32_e32 v33, 1.0, v33
	v_rcp_f32_e32 v32, v32
	v_rcp_f32_e32 v33, v33
	v_pk_mul_f32 v[38:39], v[38:39], v[48:49] op_sel_hi:[1,0]
	v_pk_mul_f32 v[40:41], v[40:41], v[48:49] op_sel_hi:[1,0]
	v_mul_f32_e32 v32, v44, v32
	v_mul_f32_e32 v33, v45, v33
	v_mul_f32_e32 v32, v36, v32
	v_mul_f32_e32 v33, v37, v33
	v_cvt_pk_bf16_f32 v32, v32, v33
	v_mul_f32_e32 v33, 0xbfb8aa3b, v46
	v_mul_f32_e32 v36, 0xbfb8aa3b, v47
	v_exp_f32_e32 v33, v33
	v_exp_f32_e32 v36, v36
	v_pk_mul_f32 v[42:43], v[42:43], v[48:49] op_sel_hi:[1,0]
	v_add_f32_e32 v33, 1.0, v33
	v_add_f32_e32 v36, 1.0, v36
	v_rcp_f32_e32 v33, v33
	v_rcp_f32_e32 v36, v36
	v_mul_f32_e32 v33, v46, v33
	v_mul_f32_e32 v36, v47, v36
	v_mul_f32_e32 v33, v38, v33
	v_mul_f32_e32 v36, v39, v36
	v_cvt_pk_bf16_f32 v33, v33, v36
	v_mul_f32_e32 v36, 0xbfb8aa3b, v40
	v_exp_f32_e32 v36, v36
	s_nop 0
	v_add_f32_e32 v36, 1.0, v36
	v_rcp_f32_e32 v36, v36
	s_nop 0
	v_mul_f32_e32 v36, v40, v36
	v_mul_f32_e32 v34, v34, v36
	v_mul_f32_e32 v36, 0xbfb8aa3b, v41
	v_exp_f32_e32 v36, v36
	s_nop 0
	v_add_f32_e32 v36, 1.0, v36
	v_rcp_f32_e32 v36, v36
	s_nop 0
	v_mul_f32_e32 v36, v41, v36
	v_mul_f32_e32 v35, v35, v36
	v_cvt_pk_bf16_f32 v34, v34, v35
	v_mul_f32_e32 v35, 0xbfb8aa3b, v42
	v_mul_f32_e32 v36, 0xbfb8aa3b, v43
	v_exp_f32_e32 v35, v35
	v_exp_f32_e32 v36, v36
	v_add_f32_e32 v35, 1.0, v35
	v_add_f32_e32 v36, 1.0, v36
	v_rcp_f32_e32 v35, v35
	v_rcp_f32_e32 v36, v36
	v_mul_f32_e32 v35, v42, v35
	v_mul_f32_e32 v36, v43, v36
	v_mul_f32_e32 v35, v50, v35
	v_mul_f32_e32 v36, v51, v36
	v_cvt_pk_bf16_f32 v35, v35, v36
	v_mad_i64_i32 v[36:37], s[18:19], v49, s41, v[114:115]
	v_lshl_add_u64 v[36:37], v[36:37], 0, v[116:117]
	global_store_dwordx4 v[36:37], v[32:35], off
	ds_read_b32 v32, v147 offset:640
	s_nop 0
	v_add_u32_e32 v33, 0xa0, v148
	s_waitcnt lgkmcnt(0)
; __device__ __forceinline__ unsigned cvt_pk_bf16(float lo, float hi) { unsigned r; asm volatile("v_cvt_pk_bf16_f32 %0, %1, %2" : "=v"(r) : "v"(lo), "v"(hi)); return r; }
; #define PG8_BAR __builtin_amdgcn_s_barrier()
; template <class Epi, class Sched, bool ALIGN_EPI = false, bool SP2 = false, bool HALFM = false>
; __device__ __forceinline__ void gemm_phase(PG8_LAS unsigned char* lds, const Gemm g, const Sched& S, const Epi& E) {
;     ...
;         if (!has_next) break;
; #pragma unroll
;         for (int a = 0; a < 2; ++a)
; #pragma unroll
;             for (int b = 0; b < 2; ++b)
; #pragma unroll
;                 for (int m = 0; m < 4; ++m)
; #pragma unroll
;                     for (int n = 0; n < 2; ++n) acc[a][b][m][n] = (f32x4){0.f, 0.f, 0.f, 0.f};
;         cur = nxt; cA = nA; cB = nB; ++ui;
;         if constexpr (ALIGN_EPI) { if (wr == 1) PG8_BAR; }
;     }
;     __device__ __forceinline__ void operator()(const f32x4 (&acc)[2][2][4][2], const Unit& u, int wr, int wc, int fr, int fq) const {
;         const int row0 = u.pm * BM + u.roff + wr * 64 + fr, col0 = u.pn * HALF + wc * 32 + 8 * fq;
; #pragma unroll
;         for (int ai = 0; ai < NAI; ++ai)
; #pragma unroll
;             for (int m = 0; m < 4; ++m) {
;                 const int row = row0 + ai * HALF + m * 16; const float ri = tab[u.par * 256 + ai * HALF + wr * 64 + m * 16 + fr];
;                 const f32x4 g0 = acc[ai][0][m][0] * ri, g1 = acc[ai][0][m][1] * ri, u0 = acc[ai][1][m][0] * ri, u1 = acc[ai][1][m][1] * ri;
;                 u32x4 w;
;                 w.x = pg8::cvt_pk_bf16(silu_mul(g0[0], u0[0]), silu_mul(g0[1], u0[1])); w.y = pg8::cvt_pk_bf16(silu_mul(g0[2], u0[2]), silu_mul(g0[3], u0[3]));
;                 w.z = pg8::cvt_pk_bf16(silu_mul(g1[0], u1[0]), silu_mul(g1[1], u1[1])); w.w = pg8::cvt_pk_bf16(silu_mul(g1[2], u1[2]), silu_mul(g1[3], u1[3]));
;                 *(u32x4*)(O + (size_t)row * DFF + col0) = w;
;                 if (m & 1) asm volatile("" ::: "memory");
;             }
	v_pk_mul_f32 v[28:29], v[28:29], v[32:33] op_sel_hi:[1,0]
	v_pk_mul_f32 v[34:35], v[18:19], v[32:33] op_sel_hi:[1,0]
	v_pk_mul_f32 v[18:19], v[16:17], v[32:33] op_sel_hi:[1,0]
	v_mul_f32_e32 v16, 0xbfb8aa3b, v28
	v_mul_f32_e32 v17, 0xbfb8aa3b, v29
	v_exp_f32_e32 v16, v16
	v_exp_f32_e32 v17, v17
	v_pk_mul_f32 v[20:21], v[20:21], v[32:33] op_sel_hi:[1,0]
	v_pk_mul_f32 v[30:31], v[30:31], v[32:33] op_sel_hi:[1,0]
	v_add_f32_e32 v16, 1.0, v16
	v_add_f32_e32 v17, 1.0, v17
	v_rcp_f32_e32 v16, v16
	v_rcp_f32_e32 v17, v17
	v_pk_mul_f32 v[22:23], v[22:23], v[32:33] op_sel_hi:[1,0]
	v_pk_mul_f32 v[24:25], v[24:25], v[32:33] op_sel_hi:[1,0]
	v_mul_f32_e32 v16, v28, v16
	v_mul_f32_e32 v17, v29, v17
	v_mul_f32_e32 v16, v20, v16
	v_mul_f32_e32 v17, v21, v17
	v_cvt_pk_bf16_f32 v16, v16, v17
	v_mul_f32_e32 v17, 0xbfb8aa3b, v30
	v_mul_f32_e32 v20, 0xbfb8aa3b, v31
	v_exp_f32_e32 v17, v17
	v_exp_f32_e32 v20, v20
	v_pk_mul_f32 v[26:27], v[26:27], v[32:33] op_sel_hi:[1,0]
	v_add_f32_e32 v17, 1.0, v17
	v_add_f32_e32 v20, 1.0, v20
	v_rcp_f32_e32 v17, v17
	v_rcp_f32_e32 v20, v20
	v_mul_f32_e32 v17, v30, v17
	v_mul_f32_e32 v20, v31, v20
	v_mul_f32_e32 v17, v22, v17
	v_mul_f32_e32 v20, v23, v20
	v_cvt_pk_bf16_f32 v17, v17, v20
	v_mul_f32_e32 v20, 0xbfb8aa3b, v24
	v_exp_f32_e32 v20, v20
	s_nop 0
	v_add_f32_e32 v20, 1.0, v20
	v_rcp_f32_e32 v20, v20
	s_nop 0
	v_mul_f32_e32 v20, v24, v20
	v_mul_f32_e32 v18, v18, v20
	v_mul_f32_e32 v20, 0xbfb8aa3b, v25
	v_exp_f32_e32 v20, v20
	s_nop 0
	v_add_f32_e32 v20, 1.0, v20
	v_rcp_f32_e32 v20, v20
	s_nop 0
	v_mul_f32_e32 v20, v25, v20
	v_mul_f32_e32 v19, v19, v20
	v_cvt_pk_bf16_f32 v18, v18, v19
	v_mul_f32_e32 v19, 0xbfb8aa3b, v26
	v_mul_f32_e32 v20, 0xbfb8aa3b, v27
	v_exp_f32_e32 v19, v19
	v_exp_f32_e32 v20, v20
	v_add_f32_e32 v19, 1.0, v19
	v_add_f32_e32 v20, 1.0, v20
	v_rcp_f32_e32 v19, v19
	v_rcp_f32_e32 v20, v20
	v_mul_f32_e32 v19, v26, v19
	v_mul_f32_e32 v20, v27, v20
	v_mul_f32_e32 v19, v34, v19
	v_mul_f32_e32 v20, v35, v20
	v_cvt_pk_bf16_f32 v19, v19, v20
	v_mad_i64_i32 v[20:21], s[18:19], v33, s41, v[114:115]
	v_lshl_add_u64 v[20:21], v[20:21], 0, v[116:117]
	global_store_dwordx4 v[20:21], v[16:19], off
	ds_read_b32 v16, v147 offset:704
	s_nop 0
	v_add_u32_e32 v17, 0xb0, v148
	s_waitcnt lgkmcnt(0)
	v_pk_mul_f32 v[12:13], v[12:13], v[16:17] op_sel_hi:[1,0]
	v_pk_mul_f32 v[18:19], v[2:3], v[16:17] op_sel_hi:[1,0]
	v_pk_mul_f32 v[2:3], v[0:1], v[16:17] op_sel_hi:[1,0]
	v_mul_f32_e32 v0, 0xbfb8aa3b, v12
	v_mul_f32_e32 v1, 0xbfb8aa3b, v13
	v_exp_f32_e32 v0, v0
	v_exp_f32_e32 v1, v1
	v_pk_mul_f32 v[4:5], v[4:5], v[16:17] op_sel_hi:[1,0]
	v_pk_mul_f32 v[14:15], v[14:15], v[16:17] op_sel_hi:[1,0]
	v_add_f32_e32 v0, 1.0, v0
	v_add_f32_e32 v1, 1.0, v1
	v_rcp_f32_e32 v0, v0
	v_rcp_f32_e32 v1, v1
	v_pk_mul_f32 v[6:7], v[6:7], v[16:17] op_sel_hi:[1,0]
	v_pk_mul_f32 v[8:9], v[8:9], v[16:17] op_sel_hi:[1,0]
	v_mul_f32_e32 v0, v12, v0
	v_mul_f32_e32 v1, v13, v1
	v_mul_f32_e32 v0, v4, v0
	v_mul_f32_e32 v1, v5, v1
	v_cvt_pk_bf16_f32 v0, v0, v1
	v_mul_f32_e32 v1, 0xbfb8aa3b, v14
	v_mul_f32_e32 v4, 0xbfb8aa3b, v15
	v_exp_f32_e32 v1, v1
	v_exp_f32_e32 v4, v4
	v_pk_mul_f32 v[10:11], v[10:11], v[16:17] op_sel_hi:[1,0]
	v_add_f32_e32 v1, 1.0, v1
	v_add_f32_e32 v4, 1.0, v4
	v_rcp_f32_e32 v1, v1
	v_rcp_f32_e32 v4, v4
	v_mul_f32_e32 v1, v14, v1
	v_mul_f32_e32 v4, v15, v4
	v_mul_f32_e32 v1, v6, v1
	v_mul_f32_e32 v4, v7, v4
	v_cvt_pk_bf16_f32 v1, v1, v4
	v_mul_f32_e32 v4, 0xbfb8aa3b, v8
	v_exp_f32_e32 v4, v4
	s_nop 0
	v_add_f32_e32 v4, 1.0, v4
	v_rcp_f32_e32 v4, v4
	s_nop 0
	v_mul_f32_e32 v4, v8, v4
	v_mul_f32_e32 v2, v2, v4
	v_mul_f32_e32 v4, 0xbfb8aa3b, v9
	v_exp_f32_e32 v4, v4
	s_nop 0
	v_add_f32_e32 v4, 1.0, v4
	v_rcp_f32_e32 v4, v4
	s_nop 0
	v_mul_f32_e32 v4, v9, v4
	v_mul_f32_e32 v3, v3, v4
	v_cvt_pk_bf16_f32 v2, v2, v3
	v_mul_f32_e32 v3, 0xbfb8aa3b, v10
	v_mul_f32_e32 v4, 0xbfb8aa3b, v11
	v_exp_f32_e32 v3, v3
	v_exp_f32_e32 v4, v4
	v_add_f32_e32 v3, 1.0, v3
	v_add_f32_e32 v4, 1.0, v4
	v_rcp_f32_e32 v3, v3
	v_rcp_f32_e32 v4, v4
	v_mul_f32_e32 v3, v10, v3
	v_mul_f32_e32 v4, v11, v4
	v_mul_f32_e32 v3, v18, v3
	v_mul_f32_e32 v4, v19, v4
	v_cvt_pk_bf16_f32 v3, v3, v4
	v_mad_i64_i32 v[4:5], s[18:19], v17, s41, v[114:115]
	v_lshl_add_u64 v[4:5], v[4:5], 0, v[116:117]
	global_store_dwordx4 v[4:5], v[0:3], off
.Lgu_epi_half_end:
	s_mov_b64 s[18:19], -1
	s_cbranch_vccnz .LBB0_174
	s_andn2_b64 vcc, exec, s[0:1]
	s_cbranch_vccnz .LBB0_173
	s_barrier
	s_branch .LBB0_173

; __global__ void __launch_bounds__(512, 2) fwd(Args a) {
	.amdhsa_kernel _Z3fwd4Args
		.amdhsa_group_segment_fixed_size 0
		.amdhsa_private_segment_fixed_size 0
		.amdhsa_kernarg_size 440
		.amdhsa_user_sgpr_count 2
		.amdhsa_user_sgpr_dispatch_ptr 0
		.amdhsa_user_sgpr_queue_ptr 0
		.amdhsa_user_sgpr_kernarg_segment_ptr 1
		.amdhsa_user_sgpr_dispatch_id 0
		.amdhsa_user_sgpr_kernarg_preload_length 0
		.amdhsa_user_sgpr_kernarg_preload_offset 0
		.amdhsa_user_sgpr_private_segment_size 0
		.amdhsa_uses_dynamic_stack 0
		.amdhsa_enable_private_segment 0
		.amdhsa_system_sgpr_workgroup_id_x 1
		.amdhsa_system_sgpr_workgroup_id_y 0
		.amdhsa_system_sgpr_workgroup_id_z 0
		.amdhsa_system_sgpr_workgroup_info 0
		.amdhsa_system_vgpr_workitem_id 2
		.amdhsa_next_free_vgpr 256
		.amdhsa_next_free_sgpr 102
		.amdhsa_accum_offset 256
		.amdhsa_reserve_vcc 1
		.amdhsa_float_round_mode_32 0
		.amdhsa_float_round_mode_16_64 0
		.amdhsa_float_denorm_mode_32 3
		.amdhsa_float_denorm_mode_16_64 3
		.amdhsa_dx10_clamp 1
		.amdhsa_ieee_mode 1
		.amdhsa_fp16_overflow 0
		.amdhsa_tg_split 0
		.amdhsa_exception_fp_ieee_invalid_op 0
		.amdhsa_exception_fp_denorm_src 0
		.amdhsa_exception_fp_ieee_div_zero 0
		.amdhsa_exception_fp_ieee_overflow 0
		.amdhsa_exception_fp_ieee_underflow 0
		.amdhsa_exception_fp_ieee_inexact 0
		.amdhsa_exception_int_div_zero 0
	.end_amdhsa_kernel

; __global__ void __launch_bounds__(512, 2) fwd(Args a) {
amdhsa.kernels:
  - .agpr_count:     0
    .args:
      - .offset:         0
        .size:           184
        .value_kind:     by_value
      - .offset:         184
        .size:           4
        .value_kind:     hidden_block_count_x
      - .offset:         188
        .size:           4
        .value_kind:     hidden_block_count_y
      - .offset:         192
        .size:           4
        .value_kind:     hidden_block_count_z
      - .offset:         196
        .size:           2
        .value_kind:     hidden_group_size_x
      - .offset:         198
        .size:           2
        .value_kind:     hidden_group_size_y
      - .offset:         200
        .size:           2
        .value_kind:     hidden_group_size_z
      - .offset:         202
        .size:           2
        .value_kind:     hidden_remainder_x
      - .offset:         204
        .size:           2
        .value_kind:     hidden_remainder_y
      - .offset:         206
        .size:           2
        .value_kind:     hidden_remainder_z
      - .offset:         224
        .size:           8
        .value_kind:     hidden_global_offset_x
      - .offset:         232
        .size:           8
        .value_kind:     hidden_global_offset_y
      - .offset:         240
        .size:           8
        .value_kind:     hidden_global_offset_z
      - .offset:         248
        .size:           2
        .value_kind:     hidden_grid_dims
      - .offset:         272
        .size:           8
        .value_kind:     hidden_multigrid_sync_arg
      - .offset:         304
        .size:           4
        .value_kind:     hidden_dynamic_lds_size
    .group_segment_fixed_size: 0
    .kernarg_segment_align: 8
    .kernarg_segment_size: 440
    .language:       OpenCL C
    .language_version:
      - 2
      - 0
    .max_flat_workgroup_size: 512
    .name:           _Z3fwd4Args
    .private_segment_fixed_size: 0
    .sgpr_count:     108
    .sgpr_spill_count: 338
    .symbol:         _Z3fwd4Args.kd
    .uniform_work_group_size: 1
    .uses_dynamic_stack: false
    .vgpr_count:     256
    .vgpr_spill_count: 0
    .wavefront_size: 64
